# hg<true> step 5: wait for the next chunk's loads moved from before the gn multiply to the gh register copies at the chunk end
# speedup vs baseline: 1.0025x; 1.0025x over previous
; template <bool FULL, bool STORE = true>
; __device__ __forceinline__ void hg_item(const Prm& P, LAS unsigned char* lds, int item, int wave) {
;     ...
;     float c0[8], c1[8]; unsigned qw[8], ivw[8]; u32x4 ghw0, ghw1;
;     ...
;     HG_LOADS(0);
.LBB0_838:
	s_or_b64 exec, exec, s[18:19]
	s_ashr_i32 s84, s91, 6
	s_and_b32 s18, s2, 7
	s_ashr_i32 s85, s84, 31
	s_lshl_b32 s33, s18, 21
	s_lshl_b32 s19, s54, 1
	s_lshl_b32 s87, s18, 10
	s_lshl_b64 s[52:53], s[84:85], 13
	s_lshl_b32 s18, s26, 10
	s_and_b32 s86, s19, 0x700
	s_or_b32 s18, s52, s18
	s_add_u32 s20, s18, s55
	v_lshlrev_b32_e32 v36, 1, v32
	s_addc_u32 s21, s53, 0
	s_lshl_b32 s22, s91, 4
	s_and_b32 s74, s22, 0x380
	v_ashrrev_i32_e32 v37, 31, v36
	v_lshl_add_u64 v[76:77], v[36:37], 0, s[74:75]
	v_lshlrev_b32_e32 v249, 1, v76
	v_add_u32_e32 v250, 0x1000, v249
	v_add_u32_e32 v251, 0x2000, v249
	v_add_u32_e32 v252, 0x3000, v249
	s_lshl_b64 s[20:21], s[20:21], 10
	v_lshl_add_u64 v[44:45], v[76:77], 0, s[20:21]
	v_lshlrev_b64 v[44:45], 1, v[44:45]
	v_lshl_add_u64 v[46:47], s[70:71], 0, v[44:45]
	global_load_dword v240, v[46:47], off nt
	v_lshl_add_u64 v[48:49], s[62:63], 0, v[44:45]
	global_load_dword v110, v[48:49], off nt
	v_lshl_add_u64 v[48:49], s[64:65], 0, v[44:45]
	s_mov_b64 s[20:21], 0x800
	v_ashrrev_i32_e32 v38, 3, v38
	s_mov_b32 s19, s53
	v_lshlrev_b32_e32 v43, 4, v32
	v_and_b32_e32 v94, 0x70, v43
	v_lshlrev_b32_e32 v74, 1, v94
	v_and_b32_e32 v60, 64, v108
	v_xor_b32_e32 v59, 1, v108
	v_add_u32_e32 v60, 64, v60
	v_cmp_lt_i32_e32 vcc, v59, v60
	v_lshlrev_b32_e32 v128, 4, v40
	v_readlane_b32 s46, v255, 48
	v_cndmask_b32_e32 v59, v108, v59, vcc
	v_lshlrev_b32_e32 v129, 2, v59
	v_xor_b32_e32 v59, 2, v108
	v_cmp_lt_i32_e32 vcc, v59, v60
	v_readlane_b32 s22, v255, 37
	v_readlane_b32 s24, v255, 38
	v_cndmask_b32_e32 v59, v108, v59, vcc
	v_lshlrev_b32_e32 v130, 2, v59
	v_xor_b32_e32 v59, 4, v108
	v_cmp_lt_i32_e32 vcc, v59, v60
	v_readlane_b32 s26, v255, 39
	v_readlane_b32 s28, v255, 40
	v_cndmask_b32_e32 v59, v108, v59, vcc
	v_readlane_b32 s30, v255, 41
	v_readlane_b32 s34, v255, 42
	v_readlane_b32 s36, v255, 43
	v_readlane_b32 s38, v255, 44
	v_readlane_b32 s40, v255, 45
	v_readlane_b32 s42, v255, 46
	v_readlane_b32 s44, v255, 47
	v_add_u32_e32 v96, s46, v34
	v_readlane_b32 s48, v255, 49
	v_readlane_b32 s50, v255, 50
	v_add_u32_e32 v61, s97, v34
	v_add_u32_e32 v63, s22, v34
	v_add_u32_e32 v64, s24, v34
	v_add_u32_e32 v65, s26, v34
	v_add_u32_e32 v66, s28, v34
	v_add_u32_e32 v67, s30, v34
	v_add_u32_e32 v68, s34, v34
	v_add_u32_e32 v69, s36, v34
	v_add_u32_e32 v70, s38, v34
	v_add_u32_e32 v71, s40, v34
	v_add_u32_e32 v72, s42, v34
	v_add_u32_e32 v73, s44, v34
	v_mul_lo_u32 v102, v96, s72
	v_lshlrev_b32_e32 v131, 2, v59
	v_or_b32_e32 v59, s97, v42
	v_lshlrev_b32_e32 v126, 3, v32
	v_mul_lo_u32 v58, v38, s94
	v_mul_u32_u24_e32 v41, 0x110, v33
	v_add_u32_e32 v58, 0, v58
	v_mad_u32_u24 v59, v59, s3, 0
	v_add_u32_e32 v133, v59, v128
	v_add_u32_e32 v156, v35, v41
	global_load_dword v111, v[48:49], off nt
	global_load_dword v241, v[46:47], off offset:2048 nt
	v_lshl_add_u64 v[46:47], v[44:45], 0, s[20:21]
	v_lshl_add_u64 v[48:49], s[62:63], 0, v[46:47]
	v_lshl_add_u64 v[46:47], s[64:65], 0, v[46:47]
	s_mov_b64 s[20:21], 0x1000
	global_load_dword v112, v[48:49], off nt
	global_load_dword v113, v[46:47], off nt
	v_lshl_add_u64 v[46:47], v[44:45], 0, s[20:21]
	v_lshl_add_u64 v[48:49], s[70:71], 0, v[46:47]
	s_mov_b64 s[20:21], 0x1800
	global_load_dword v242, v[48:49], off nt
	v_lshl_add_u64 v[48:49], s[62:63], 0, v[46:47]
	v_lshl_add_u64 v[46:47], s[64:65], 0, v[46:47]
	global_load_dword v114, v[48:49], off nt
	global_load_dword v115, v[46:47], off nt
	v_lshl_add_u64 v[46:47], v[44:45], 0, s[20:21]
	v_lshl_add_u64 v[48:49], s[70:71], 0, v[46:47]
	s_mov_b64 s[20:21], 0x2000
	global_load_dword v243, v[48:49], off nt
	v_lshl_add_u64 v[48:49], s[62:63], 0, v[46:47]
	v_lshl_add_u64 v[46:47], s[64:65], 0, v[46:47]
	global_load_dword v116, v[48:49], off nt
	global_load_dword v117, v[46:47], off nt
	v_lshl_add_u64 v[46:47], v[44:45], 0, s[20:21]
	v_lshl_add_u64 v[48:49], s[70:71], 0, v[46:47]
	s_mov_b64 s[20:21], 0x2800
	global_load_dword v244, v[48:49], off nt
	v_lshl_add_u64 v[48:49], s[62:63], 0, v[46:47]
	v_lshl_add_u64 v[46:47], s[64:65], 0, v[46:47]
	global_load_dword v118, v[48:49], off nt
	global_load_dword v119, v[46:47], off nt
	v_lshl_add_u64 v[46:47], v[44:45], 0, s[20:21]
	v_lshl_add_u64 v[48:49], s[70:71], 0, v[46:47]
	s_mov_b64 s[20:21], 0x3000
	global_load_dword v245, v[48:49], off nt
	v_lshl_add_u64 v[48:49], s[62:63], 0, v[46:47]
	v_lshl_add_u64 v[46:47], s[64:65], 0, v[46:47]
	global_load_dword v120, v[48:49], off nt
	global_load_dword v121, v[46:47], off nt
	v_lshl_add_u64 v[46:47], v[44:45], 0, s[20:21]
	v_lshl_add_u64 v[48:49], s[70:71], 0, v[46:47]
	s_mov_b64 s[20:21], 0x3800
	v_lshl_add_u64 v[44:45], v[44:45], 0, s[20:21]
	v_readlane_b32 s20, v255, 36
	global_load_dword v246, v[48:49], off nt
	v_lshl_add_u64 v[48:49], s[62:63], 0, v[46:47]
	v_lshl_add_u64 v[46:47], s[64:65], 0, v[46:47]
	global_load_dword v122, v[48:49], off nt
	global_load_dword v123, v[46:47], off nt
	v_lshl_add_u64 v[46:47], s[70:71], 0, v[44:45]
	v_add_u32_e32 v62, s20, v34
	global_load_dword v247, v[46:47], off nt
	v_lshl_add_u64 v[46:47], s[62:63], 0, v[44:45]
	v_lshl_add_u64 v[44:45], s[64:65], 0, v[44:45]
	global_load_dword v124, v[46:47], off nt
	global_load_dword v125, v[44:45], off nt
	v_lshlrev_b32_e32 v47, 2, v32
	v_ashrrev_i32_e32 v39, 31, v38
	v_lshl_add_u64 v[44:45], s[18:19], 0, v[38:39]
	v_lshlrev_b64 v[44:45], 11, v[44:45]
	v_lshl_add_u64 v[44:45], s[66:67], 0, v[44:45]
	s_lshl_b32 s18, s74, 1
	s_mov_b32 s19, s75
	v_lshl_add_u64 v[44:45], v[44:45], 0, s[18:19]
	v_lshl_add_u64 v[44:45], v[44:45], 0, v[74:75]
	global_load_dwordx4 v[48:51], v[44:45], off offset:16 nt
	global_load_dwordx4 v[52:55], v[44:45], off nt
	s_movk_i32 s18, 0x120
; #define LAS __attribute__((address_space(3)))
; template <bool FULL, bool STORE = true>
; __device__ __forceinline__ void hg_item(const Prm& P, LAS unsigned char* lds, int item, int wave) {
;     ...
;     HG_LOADS(0);
;     for (int ch = 0; ch < 16; ++ch) {
;         const size_t row0 = (size_t)b * SEQ + seg * 1024 + ch * 64;
;         float ka[8], kc[8], f0[8], f1[8]; float t0 = 0.f, t1 = 0.f;
; #pragma unroll
;         for (int i = 0; i < 8; ++i) { f0[i] = __expf(c0[i]); f1[i] = __expf(c1[i]); ka[i] = 1.0f - f0[i]; kc[i] = 1.0f - f1[i]; t0 += c0[i]; t1 += c1[i]; }
;         *(LAS f32x2*)(lds + HL_TOT + (tg * 128 + k2) * 4) = (f32x2){t0, t1};
	v_mul_lo_u32 v127, v32, s18
	v_readlane_b32 s18, v255, 32
	s_add_i32 s19, 0, 0x15c00
	s_lshl_b32 s74, s74, 2
	v_or_b32_e32 v45, s18, v42
	s_add_i32 s18, 0, 0x11400
	v_mov_b32_e32 v40, s18
	v_add_u32_e32 v57, s18, v128
	v_readlane_b32 s18, v255, 34
	v_mov_b32_e32 v46, s19
	v_add_u32_e32 v74, s59, v34
	v_readlane_b32 s19, v255, 33
	v_or_b32_e32 v95, s18, v42
	v_or_b32_e32 v221, s97, v42
	v_mul_u32_u24_e32 v222, s72, v221
	v_add_lshl_u32 v223, v34, s18, 1
	v_add3_u32 v222, v222, v223, s73
	v_add_u32_e32 v221, s97, v221
	v_subrev_u32_e32 v221, s18, v221
	s_add_u32 vcc_lo, s82, s74
	v_mad_u32_u24 v40, v45, s72, v40
	v_mad_u32_u24 v45, v45, s3, v46
	v_lshl_add_u32 v46, v42, 2, s19
	v_readlane_b32 s19, v255, 29
	v_cmp_lt_i32_e64 s[46:47], v221, v96
	v_add_u32_e32 v96, s48, v34
	v_add_u32_e32 v34, s50, v34
	v_mul_lo_u32 v104, v74, s94
	v_lshlrev_b32_e32 v74, 2, v94
	s_addc_u32 vcc_hi, s83, 0
	v_or_b32_e32 v44, s59, v42
	v_or_b32_e32 v56, s19, v42
	v_mad_u32_u24 v60, v95, s3, 0
	v_lshl_add_u32 v42, v95, 1, s73
	v_cmp_lt_i32_e64 s[18:19], v221, v61
	v_cmp_lt_i32_e64 s[20:21], v221, v62
	v_cmp_lt_i32_e64 s[22:23], v221, v63
	v_cmp_lt_i32_e64 s[24:25], v221, v64
	v_cmp_lt_i32_e64 s[26:27], v221, v65
	v_cmp_lt_i32_e64 s[28:29], v221, v66
	v_cmp_lt_i32_e64 s[30:31], v221, v67
	v_cmp_lt_i32_e64 s[34:35], v221, v68
	v_cmp_lt_i32_e64 s[36:37], v221, v69
	v_cmp_lt_i32_e64 s[38:39], v221, v70
	v_cmp_lt_i32_e64 s[40:41], v221, v71
	v_cmp_lt_i32_e64 s[42:43], v221, v72
	v_cmp_lt_i32_e64 s[44:45], v221, v73
	v_cmp_lt_i32_e64 s[48:49], v221, v96
	v_cmp_lt_i32_e64 s[50:51], v221, v34
	v_lshl_add_u64 v[94:95], vcc, 0, v[74:75]
	s_lshl_b64 vcc, s[84:85], 24
	s_or_b32 vcc_lo, vcc_lo, s33
	v_readlane_b32 s33, v255, 55
	s_add_u32 s33, s33, s52
	s_addc_u32 s53, s90, s53
	v_lshlrev_b64 v[38:39], 11, v[38:39]
	v_and_b32_e32 v32, 7, v32
	s_add_u32 s52, s33, s87
	v_lshl_add_u64 v[38:39], vcc, 0, v[38:39]
	v_lshlrev_b32_e32 v32, 5, v32
	s_addc_u32 s53, s53, 0
	s_or_b32 s33, vcc_lo, s86
	v_mul_lo_u32 v43, v44, s72
	v_mul_lo_u32 v44, v44, s3
	v_mul_lo_u32 v56, v56, s72
	v_mul_lo_u32 v105, v34, s72
	v_mul_u32_u24_e32 v34, 0x90, v33
	v_or3_b32 v38, v38, s86, v32
	v_mov_b32_e32 v32, s33
	v_mov_b32_e32 v33, vcc_hi
	v_add_u32_e32 v43, s73, v43
	v_add_u32_e32 v44, 0, v44
	v_add_u32_e32 v56, 0, v56
	v_mul_lo_u32 v61, v61, s72
	v_mul_lo_u32 v62, v62, s72
	v_mul_lo_u32 v63, v63, s72
	v_mul_lo_u32 v64, v64, s72
	v_mul_lo_u32 v65, v65, s72
	v_mul_lo_u32 v66, v66, s72
	v_mul_lo_u32 v67, v67, s72
	v_mul_lo_u32 v68, v68, s72
	v_mul_lo_u32 v69, v69, s72
	v_mul_lo_u32 v70, v70, s72
	v_mul_lo_u32 v71, v71, s72
	v_mul_lo_u32 v72, v72, s72
	v_mul_lo_u32 v73, v73, s72
	v_mul_lo_u32 v103, v96, s72
	v_lshl_add_u64 v[32:33], v[36:37], 1, v[32:33]
	v_readlane_b32 s33, v255, 51
	v_mov_b32_e32 v253, v38
	v_lshl_add_u64 v[96:97], s[92:93], 0, v[38:39]
	s_lshl_b64 s[84:85], s[52:53], 10
	v_lshl_add_u64 v[98:99], s[78:79], 0, v[32:33]
	v_lshl_add_u64 v[100:101], s[80:81], 0, v[32:33]
	s_mov_b64 s[86:87], 0
	v_add_u32_e32 v132, s33, v47
	v_add_u32_e32 v134, v60, v128
	v_add_u32_e32 v135, v42, v61
	v_add_u32_e32 v136, v42, v62
	v_add_u32_e32 v137, v42, v63
	v_add_u32_e32 v138, v42, v64
	v_add_u32_e32 v139, v42, v65
	v_add_u32_e32 v140, v42, v66
	v_add_u32_e32 v141, v42, v67
	v_add_u32_e32 v142, v42, v68
	v_add_u32_e32 v143, v42, v69
	v_add_u32_e32 v144, v42, v70
	v_add_u32_e32 v145, v42, v71
	v_add_u32_e32 v146, v42, v72
	v_add_u32_e32 v147, v42, v73
	v_add_u32_e32 v148, v42, v102
	v_add_u32_e32 v149, v42, v103
	v_add_u32_e32 v150, v42, v105
	v_add_u32_e32 v151, v44, v128
	v_add_u32_e32 v152, v45, v128
	v_add_u32_e32 v153, v46, v104
	v_add_u32_e32 v154, v56, v128
	v_add_u32_e32 v155, v57, v34
	v_add_u32_e32 v157, v58, v74
	v_add_u32_e32 v158, v43, v128
	v_add_u32_e32 v159, v40, v128
	global_load_dwordx4 v[224:227], v[94:95], off offset:48
	global_load_dwordx4 v[228:231], v[94:95], off offset:32
	global_load_dwordx4 v[232:235], v[94:95], off offset:16
	global_load_dwordx4 v[236:239], v[94:95], off
	s_waitcnt vmcnt(8)
	v_cvt_f32_f16_e32 v78, v240
	v_cvt_f32_f16_sdwa v79, v240 dst_sel:DWORD dst_unused:UNUSED_PAD src0_sel:WORD_1
	v_cvt_f32_f16_e32 v80, v241
	v_cvt_f32_f16_sdwa v81, v241 dst_sel:DWORD dst_unused:UNUSED_PAD src0_sel:WORD_1
	v_cvt_f32_f16_e32 v82, v242
	v_cvt_f32_f16_sdwa v83, v242 dst_sel:DWORD dst_unused:UNUSED_PAD src0_sel:WORD_1
	v_cvt_f32_f16_e32 v84, v243
	v_cvt_f32_f16_sdwa v85, v243 dst_sel:DWORD dst_unused:UNUSED_PAD src0_sel:WORD_1
	v_cvt_f32_f16_e32 v86, v244
	v_cvt_f32_f16_sdwa v87, v244 dst_sel:DWORD dst_unused:UNUSED_PAD src0_sel:WORD_1
	v_cvt_f32_f16_e32 v88, v245
	v_cvt_f32_f16_sdwa v89, v245 dst_sel:DWORD dst_unused:UNUSED_PAD src0_sel:WORD_1
	v_cvt_f32_f16_e32 v90, v246
	v_cvt_f32_f16_sdwa v91, v246 dst_sel:DWORD dst_unused:UNUSED_PAD src0_sel:WORD_1
	v_cvt_f32_f16_e32 v92, v247
	v_cvt_f32_f16_sdwa v93, v247 dst_sel:DWORD dst_unused:UNUSED_PAD src0_sel:WORD_1
	s_nop 0
	v_pk_add_f32 v[32:33], v[78:79], 0 op_sel_hi:[1,0]
	v_pk_add_f32 v[32:33], v[32:33], v[80:81]
	v_pk_add_f32 v[32:33], v[32:33], v[82:83]
	v_pk_add_f32 v[32:33], v[32:33], v[84:85]
	v_pk_add_f32 v[32:33], v[32:33], v[86:87]
	v_pk_add_f32 v[32:33], v[32:33], v[88:89]
	v_pk_add_f32 v[32:33], v[32:33], v[90:91]
	v_pk_add_f32 v[32:33], v[32:33], v[92:93]
	v_add_u32_e32 v36, s60, v126
	s_waitcnt vmcnt(0)
	ds_write_b64 v36, v[32:33]
	s_waitcnt lgkmcnt(0)
	s_barrier
	s_branch .LBB0_840
; #define LAS __attribute__((address_space(3)))
; template <bool FULL, bool STORE = true>
; __device__ __forceinline__ void hg_item(const Prm& P, LAS unsigned char* lds, int item, int wave) {
;     ...
;                 for (int ks = 0; ks < 8; ++ks) { const bf16x8 a = *(const LAS bf16x8*)(lds + HL_QD + (tb * 32 + l31) * 272 + ks * 32 + lh * 16), bb = *(const LAS bf16x8*)(lds + HL_ST + (vb * 32 + l31) * 272 + ks * 32 + lh * 16);
;                     o = __builtin_amdgcn_mfma_f32_32x32x16_bf16(a, bb, o, 0, 0, 0); }
; #pragma unroll
;                 for (int r = 0; r < 16; ++r) { const int t = tb * 32 + (r & 3) + 8 * (r >> 2) + 4 * lh; *(LAS float*)(lds + HL_OS + t * 528 + (vb * 32 + l31) * 4) = o[r]; }
;             }
;         }
; #pragma unroll
;         for (int g4 = 0; g4 < 4; ++g4) { const f32x4 d = *(const LAS f32x4*)(lds + HL_DC + (kb * 32 + 8 * g4 + 4 * lh) * 4);
; #pragma unroll
;             for (int i = 0; i < 2; ++i)
; #pragma unroll
;                 for (int j = 0; j < 4; ++j) S[i][4 * g4 + j] *= d[j]; }
.LBB0_839:
	s_mov_b32 s33, 0x800000
	s_add_u32 s86, s86, 0x20000
	s_addc_u32 s87, s87, 0
	v_lshlrev_b32_e32 v104, 16, v52
	v_and_b32_e32 v105, 0xffff0000, v52
	v_lshlrev_b32_e32 v52, 16, v53
	v_and_b32_e32 v53, 0xffff0000, v53
	s_add_u32 s84, s84, 0x10000
	s_addc_u32 s85, s85, 0
	s_cmp_lg_u32 s86, 0x200000
	s_waitcnt lgkmcnt(6)
	v_mfma_f32_32x32x16_bf16 v[32:47], v[172:175], v[176:179], v[32:47]
	ds_read_b128 v[172:175], v151 offset:34944
	ds_read_b128 v[176:179], v152 offset:128
	v_pk_mul_f32 v[0:1], v[0:1], v[78:79]
	v_pk_mul_f32 v[2:3], v[2:3], v[80:81]
	s_waitcnt lgkmcnt(6)
	v_mfma_f32_32x32x16_bf16 v[32:47], v[180:183], v[184:187], v[32:47]
	ds_read_b128 v[180:183], v151 offset:34976
	ds_read_b128 v[184:187], v152 offset:160
	v_pk_mul_f32 v[16:17], v[16:17], v[78:79]
	v_pk_mul_f32 v[18:19], v[18:19], v[80:81]
	s_waitcnt lgkmcnt(6)
	v_mfma_f32_32x32x16_bf16 v[32:47], v[188:191], v[192:195], v[32:47]
	ds_read_b128 v[188:191], v151 offset:35008
	ds_read_b128 v[192:195], v152 offset:192
	v_pk_mul_f32 v[4:5], v[4:5], v[82:83]
	v_pk_mul_f32 v[6:7], v[6:7], v[84:85]
	s_waitcnt lgkmcnt(6)
	v_mfma_f32_32x32x16_bf16 v[32:47], v[196:199], v[200:203], v[32:47]
	ds_read_b128 v[196:199], v151 offset:35040
	ds_read_b128 v[200:203], v152 offset:224
	ds_read_b128 v[204:207], v155 offset:4608
	ds_read_b128 v[208:211], v155 offset:4640
	ds_read_b128 v[212:215], v155 offset:4672
	ds_read_b128 v[216:219], v155 offset:4704
	v_pk_mul_f32 v[20:21], v[20:21], v[82:83]
	v_pk_mul_f32 v[22:23], v[22:23], v[84:85]
	s_waitcnt lgkmcnt(10)
	v_mfma_f32_32x32x16_bf16 v[32:47], v[172:175], v[176:179], v[32:47]
	v_pk_mul_f32 v[8:9], v[8:9], v[86:87]
	v_pk_mul_f32 v[10:11], v[10:11], v[88:89]
	ds_read_b128 v[172:175], v154 offset:52224
	ds_read_b128 v[176:179], v154 offset:52256
	s_waitcnt lgkmcnt(10)
	v_mfma_f32_32x32x16_bf16 v[32:47], v[180:183], v[184:187], v[32:47]
	v_pk_mul_f32 v[24:25], v[24:25], v[86:87]
	v_pk_mul_f32 v[26:27], v[26:27], v[88:89]
	ds_read_b128 v[180:183], v154 offset:52288
	ds_read_b128 v[184:187], v154 offset:52320
	s_waitcnt lgkmcnt(10)
	v_mfma_f32_32x32x16_bf16 v[32:47], v[188:191], v[192:195], v[32:47]
	v_pk_mul_f32 v[12:13], v[12:13], v[90:91]
	v_pk_mul_f32 v[14:15], v[14:15], v[92:93]
	ds_read_b128 v[188:191], v155
	ds_read_b128 v[192:195], v155 offset:32
	s_waitcnt lgkmcnt(10)
	v_mfma_f32_32x32x16_bf16 v[32:47], v[196:199], v[200:203], v[32:47]
	v_pk_mul_f32 v[28:29], v[28:29], v[90:91]
	v_pk_mul_f32 v[30:31], v[30:31], v[92:93]
	ds_read_b128 v[196:199], v155 offset:64
	ds_read_b128 v[200:203], v155 offset:96
	s_nop 11
	ds_write2_b32 v153, v32, v33 offset1:132
	v_add_u32_e32 v32, 0x400, v153
	ds_write2_b32 v32, v34, v35 offset0:8 offset1:140
	v_add_u32_e32 v32, 0x1000, v153
	ds_write2_b32 v32, v36, v37 offset0:32 offset1:164
	v_add_u32_e32 v32, 0x1400, v153
	ds_write2_b32 v32, v38, v39 offset0:40 offset1:172
	v_add_u32_e32 v32, 0x2000, v153
	ds_write2_b32 v32, v40, v41 offset0:64 offset1:196
	v_add_u32_e32 v32, 0x2400, v153
	ds_write2_b32 v32, v42, v43 offset0:72 offset1:204
	v_add_u32_e32 v32, 0x3000, v153
	ds_write2_b32 v32, v44, v45 offset0:96 offset1:228
	v_add_u32_e32 v32, 0x3400, v153
	ds_write2_b32 v32, v46, v47 offset0:104 offset1:236
	s_waitcnt vmcnt(18)
	v_cvt_f32_f16_e32 v78, v240
	v_cvt_f32_f16_sdwa v79, v240 dst_sel:DWORD dst_unused:UNUSED_PAD src0_sel:WORD_1
	v_cvt_f32_f16_e32 v80, v241
	v_cvt_f32_f16_sdwa v81, v241 dst_sel:DWORD dst_unused:UNUSED_PAD src0_sel:WORD_1
	v_cvt_f32_f16_e32 v82, v242
	v_cvt_f32_f16_sdwa v83, v242 dst_sel:DWORD dst_unused:UNUSED_PAD src0_sel:WORD_1
	v_cvt_f32_f16_e32 v84, v243
	v_cvt_f32_f16_sdwa v85, v243 dst_sel:DWORD dst_unused:UNUSED_PAD src0_sel:WORD_1
	v_cvt_f32_f16_e32 v86, v244
	v_cvt_f32_f16_sdwa v87, v244 dst_sel:DWORD dst_unused:UNUSED_PAD src0_sel:WORD_1
	v_cvt_f32_f16_e32 v88, v245
	v_cvt_f32_f16_sdwa v89, v245 dst_sel:DWORD dst_unused:UNUSED_PAD src0_sel:WORD_1
	v_cvt_f32_f16_e32 v90, v246
	v_cvt_f32_f16_sdwa v91, v246 dst_sel:DWORD dst_unused:UNUSED_PAD src0_sel:WORD_1
	v_cvt_f32_f16_e32 v92, v247
	v_cvt_f32_f16_sdwa v93, v247 dst_sel:DWORD dst_unused:UNUSED_PAD src0_sel:WORD_1
	s_nop 0
	v_pk_add_f32 v[32:33], v[78:79], 0 op_sel_hi:[1,0]
	v_pk_add_f32 v[32:33], v[32:33], v[80:81]
	v_pk_add_f32 v[32:33], v[32:33], v[82:83]
	v_pk_add_f32 v[32:33], v[32:33], v[84:85]
	v_pk_add_f32 v[32:33], v[32:33], v[86:87]
	v_pk_add_f32 v[32:33], v[32:33], v[88:89]
	v_pk_add_f32 v[32:33], v[32:33], v[90:91]
	v_pk_add_f32 v[32:33], v[32:33], v[92:93]
	v_add_u32_e32 v36, s60, v126
	ds_write_b64 v36, v[32:33]
	s_waitcnt lgkmcnt(0)
	s_barrier
; #define LAS __attribute__((address_space(3)))
; __device__ __forceinline__ unsigned pk2(float lo, float hi) { typedef float f2v __attribute__((ext_vector_type(2))); typedef __bf16 b2v __attribute__((ext_vector_type(2))); const f2v v = {lo, hi}; const b2v b = __builtin_convertvector(v, b2v); return __builtin_bit_cast(unsigned, b); }
; template <bool FULL, bool STORE = true>
; __device__ __forceinline__ void hg_item(const Prm& P, LAS unsigned char* lds, int item, int wave) {
;     ...
;         for (int ks = 0; ks < 4; ++ks) { const bf16x8 a = *(const LAS bf16x8*)(lds + HL_KDT + (kb * 32 + l31) * 144 + ks * 32 + lh * 16);
; #pragma unroll
;             for (int i = 0; i < 2; ++i) { const bf16x8 bb = *(const LAS bf16x8*)(lds + HL_IVT + ((vb0 + i) * 32 + l31) * 144 + ks * 32 + lh * 16); S[i] = __builtin_amdgcn_mfma_f32_32x32x16_bf16(a, bb, S[i], 0, 0, 0); } }
;         if (FULL) {
;             __syncthreads();
; #pragma unroll
;             for (int i = 0; i < 2; ++i)
; #pragma unroll
;                 for (int g4 = 0; g4 < 4; ++g4) { u32x2 w; w.x = pk2(S[i][4 * g4], S[i][4 * g4 + 1]); w.y = pk2(S[i][4 * g4 + 2], S[i][4 * g4 + 3]);
;                     *(LAS u32x2*)(lds + HL_ST + ((vb0 + i) * 32 + l31) * 272 + (kb * 32 + 8 * g4 + 4 * lh) * 2) = w; }
;             { const int t = tid >> 3, vs = (tid & 7) * 16; float o[16]; float ss = 0.f;
; #pragma unroll
;                 for (int q4 = 0; q4 < 4; ++q4) { const f32x4 x4 = *(const LAS f32x4*)(lds + HL_OS + t * 528 + (vs + 4 * q4) * 4);
; #pragma unroll
;                     for (int j = 0; j < 4; ++j) { o[4 * q4 + j] = x4[j]; ss += x4[j] * x4[j]; } }
;                 ss += __shfl_xor(ss, 1); ss += __shfl_xor(ss, 2); ss += __shfl_xor(ss, 4);
;                 const float r = rsqrtf(ss * (1.0f / 128.0f) + EPS);
;                 const size_t oo = (row0 + t) * 1024 + h * 128 + vs; const float* gn = P.in[I_HGNG] + h * 128 + vs;
;                 float g0[8], g1[8]; unpack8(gcur0, g0); unpack8(gcur1, g1);
;                 float w0[8], w1[8];
; #pragma unroll
;                 for (int j = 0; j < 8; ++j) { w0[j] = o[j] * r * gn[j] * g0[j]; w1[j] = o[8 + j] * r * gn[8 + j] * g1[j]; }
;                 if (STORE) { *(u32x4*)(AHG + oo) = pack8(w0); *(u32x4*)(AHG + oo + 8) = pack8(w1); }
;             }
	ds_read_b128 v[66:69], v157
	ds_read_b128 v[36:39], v157 offset:16
	ds_read_b128 v[44:47], v157 offset:32
	ds_read_b128 v[32:35], v157 offset:48
	s_waitcnt lgkmcnt(3)
	v_mul_f32_e32 v64, v67, v67
	v_mfma_f32_32x32x16_bf16 v[0:15], v[172:175], v[188:191], v[0:15]
	v_fmac_f32_e32 v64, v66, v66
	v_fmac_f32_e32 v64, v68, v68
	v_fmac_f32_e32 v64, v69, v69
	s_waitcnt lgkmcnt(2)
	v_fmac_f32_e32 v64, v36, v36
	v_fmac_f32_e32 v64, v37, v37
	v_fmac_f32_e32 v64, v38, v38
	v_fmac_f32_e32 v64, v39, v39
	v_mfma_f32_32x32x16_bf16 v[16:31], v[172:175], v[204:207], v[16:31]
	s_waitcnt lgkmcnt(1)
	v_pk_mul_f32 v[42:43], v[44:45], v[44:45]
	v_pk_mul_f32 v[40:41], v[46:47], v[46:47]
	v_add_f32_e32 v42, v42, v64
	v_add_f32_e32 v42, v43, v42
	v_add_f32_e32 v40, v40, v42
	v_add_f32_e32 v64, v41, v40
	s_waitcnt lgkmcnt(0)
	s_barrier
	v_pk_mul_f32 v[42:43], v[32:33], v[32:33]
	v_mfma_f32_32x32x16_bf16 v[0:15], v[176:179], v[192:195], v[0:15]
	v_pk_mul_f32 v[40:41], v[34:35], v[34:35]
	v_add_f32_e32 v42, v42, v64
	v_add_f32_e32 v42, v43, v42
	v_add_f32_e32 v40, v40, v42
	v_add_f32_e32 v40, v41, v40
	s_nop 1
	v_add_f32_dpp v40, v40, v40 quad_perm:[1,0,3,2] row_mask:0xf bank_mask:0xf
	s_nop 1
	v_add_f32_dpp v40, v40, v40 quad_perm:[2,3,0,1] row_mask:0xf bank_mask:0xf
	v_mfma_f32_32x32x16_bf16 v[16:31], v[176:179], v[208:211], v[16:31]
	s_nop 1
	v_add_f32_dpp v40, v40, v40 row_half_mirror row_mask:0xf bank_mask:0xf
	v_fmamk_f32 v40, v40, 0x3c000000, v109
	v_cmp_gt_f32_e32 vcc, s33, v40
	v_mul_f32_e32 v41, 0x4b800000, v40
	s_mov_b32 s33, 0x7400000
	v_cndmask_b32_e32 v40, v40, v41, vcc
	v_rsq_f32_e32 v40, v40
	s_nop 0
	v_mul_f32_e32 v41, 0x45800000, v40
	v_mfma_f32_32x32x16_bf16 v[0:15], v[180:183], v[196:199], v[0:15]
	v_cndmask_b32_e32 v74, v40, v41, vcc
	v_pk_mul_f32 v[106:107], v[66:67], v[74:75] op_sel_hi:[1,0]
	v_pk_mul_f32 v[46:47], v[46:47], v[74:75] op_sel_hi:[1,0]
	v_pk_mul_f32 v[36:37], v[36:37], v[74:75] op_sel_hi:[1,0]
	v_pk_mul_f32 v[32:33], v[32:33], v[74:75] op_sel_hi:[1,0]
	v_pk_mul_f32 v[44:45], v[44:45], v[74:75] op_sel_hi:[1,0]
	v_pk_mul_f32 v[38:39], v[38:39], v[74:75] op_sel_hi:[1,0]
	v_mfma_f32_32x32x16_bf16 v[16:31], v[180:183], v[212:215], v[16:31]
	v_pk_mul_f32 v[34:35], v[34:35], v[74:75] op_sel_hi:[1,0]
	v_pk_mul_f32 v[32:33], v[224:225], v[32:33]
	v_pk_mul_f32 v[46:47], v[230:231], v[46:47]
	v_pk_mul_f32 v[36:37], v[232:233], v[36:37]
	v_pk_mul_f32 v[106:107], v[236:237], v[106:107]
	v_pk_mul_f32 v[44:45], v[228:229], v[44:45]
	v_pk_mul_f32 v[104:105], v[106:107], v[104:105]
	v_mfma_f32_32x32x16_bf16 v[0:15], v[184:187], v[200:203], v[0:15]
	v_lshlrev_b32_e32 v106, 16, v48
	v_and_b32_e32 v107, 0xffff0000, v48
	v_lshlrev_b32_e32 v48, 16, v49
	v_and_b32_e32 v49, 0xffff0000, v49
	v_pk_mul_f32 v[46:47], v[46:47], v[48:49]
	v_lshlrev_b32_e32 v48, 16, v54
	v_and_b32_e32 v49, 0xffff0000, v54
	v_mfma_f32_32x32x16_bf16 v[16:31], v[184:187], v[216:219], v[16:31]
	v_pk_mul_f32 v[36:37], v[36:37], v[48:49]
	v_lshlrev_b32_e32 v48, 16, v50
	v_and_b32_e32 v49, 0xffff0000, v50
	v_pk_mul_f32 v[64:65], v[68:69], v[74:75] op_sel_hi:[1,0]
	v_pk_mul_f32 v[40:41], v[32:33], v[48:49]
	v_lshlrev_b32_e32 v32, 16, v55
	v_and_b32_e32 v33, 0xffff0000, v55
	v_pk_mul_f32 v[38:39], v[234:235], v[38:39]
	v_pk_mul_f32 v[64:65], v[238:239], v[64:65]
	v_pk_mul_f32 v[38:39], v[38:39], v[32:33]
	v_lshlrev_b32_e32 v32, 16, v51
	v_and_b32_e32 v33, 0xffff0000, v51
	v_pk_mul_f32 v[34:35], v[226:227], v[34:35]
	v_pk_mul_f32 v[52:53], v[64:65], v[52:53]
	v_pk_mul_f32 v[42:43], v[34:35], v[32:33]
	v_cvt_pk_bf16_f32 v34, v36, v37
	v_add_co_u32_e32 v36, vcc, s33, v102
	v_pk_mul_f32 v[44:45], v[44:45], v[106:107]
	v_cvt_pk_bf16_f32 v32, v104, v105
	v_cvt_pk_bf16_f32 v33, v52, v53
	v_cvt_pk_bf16_f32 v35, v38, v39
	v_addc_co_u32_e32 v37, vcc, 0, v103, vcc
	s_waitcnt vmcnt(0)
	v_mov_b64_e32 v[52:53], v[56:57]
	v_mov_b64_e32 v[48:49], v[60:61]
	global_store_dwordx4 v[36:37], v[32:35], off
	v_mov_b64_e32 v[54:55], v[58:59]
	v_mov_b64_e32 v[50:51], v[62:63]
	v_cvt_pk_bf16_f32 v32, v44, v45
	v_cvt_pk_bf16_f32 v33, v46, v47
	v_cvt_pk_bf16_f32 v34, v40, v41
	v_cvt_pk_bf16_f32 v35, v42, v43
	global_store_dwordx4 v[36:37], v[32:35], off offset:16
	s_nop 8
	v_cvt_pk_bf16_f32 v32, v0, v1
	v_cvt_pk_bf16_f32 v33, v2, v3
	v_cvt_pk_bf16_f32 v34, v4, v5
	v_cvt_pk_bf16_f32 v35, v6, v7
	ds_write2_b64 v156, v[32:33], v[34:35] offset1:2
	v_cvt_pk_bf16_f32 v32, v8, v9
	v_cvt_pk_bf16_f32 v33, v10, v11
	v_cvt_pk_bf16_f32 v34, v12, v13
	v_cvt_pk_bf16_f32 v35, v14, v15
	ds_write2_b64 v156, v[32:33], v[34:35] offset0:4 offset1:6
	v_cvt_pk_bf16_f32 v32, v16, v17
	v_cvt_pk_bf16_f32 v33, v18, v19
	v_cvt_pk_bf16_f32 v34, v20, v21
	v_cvt_pk_bf16_f32 v35, v22, v23
	v_add_u32_e32 v36, 0x2000, v156
	ds_write2_b64 v36, v[32:33], v[34:35] offset0:64 offset1:66
	v_cvt_pk_bf16_f32 v32, v24, v25
	v_cvt_pk_bf16_f32 v33, v26, v27
	v_cvt_pk_bf16_f32 v34, v28, v29
	v_cvt_pk_bf16_f32 v35, v30, v31
	ds_write2_b64 v36, v[32:33], v[34:35] offset0:68 offset1:70
	s_cbranch_scc0 .LBB0_821
